# stack: v33 + hand-written pass A step-1 loop + census words read together, padded so later loops keep v33's byte offsets
# speedup vs baseline: 1.0047x; 1.0015x over previous
; #define LAS __attribute__((address_space(3)))
; __device__ __forceinline__ float logsig_f(float z) { return fminf(z, 0.f) - __logf(1.f + __expf(-fabsf(z))); }
; __device__ __forceinline__ void gla_passA(LAS unsigned char* lds, int uidx, const bf16_t* PR, const float* GLRP, const float* w2, const float* gb,
;                                           bf16_t* SUB, float* EB, bf16_t* QT, bf16_t* AM, int tid, int wid, int lane) {
;     ...
;     { float run = 0.f;
; #pragma unroll 4
;       for (int i = 0; i < 16; ++i) { const int t = 16 * tg + i; const LAS f32x4* gr = (const LAS f32x4*)(Gs + t * 16); const f32x4 a0 = gr[0], a1 = gr[1], a2 = gr[2], a3 = gr[3];
;           float z = bias;
;           z += a0.x * wk[0] + a0.y * wk[1] + a0.z * wk[2] + a0.w * wk[3]; z += a1.x * wk[4] + a1.y * wk[5] + a1.z * wk[6] + a1.w * wk[7];
;           z += a2.x * wk[8] + a2.y * wk[9] + a2.z * wk[10] + a2.w * wk[11]; z += a3.x * wk[12] + a3.y * wk[13] + a3.z * wk[14] + a3.w * wk[15];
;           run += logsig_f(z) * (1.f / 16.f); Bc[t * 129 + kcol] = run; }
;       Tt[tg * 128 + kcol] = run; }
.Lpa_nopf:
.LBB0_352:
	v_add_u32_e32 v254, 0x1d700, v17
	ds_read2_b32 v[20:21], v254 offset0:0 offset1:4
	ds_read2_b32 v[22:23], v254 offset0:1 offset1:5
	ds_read2_b32 v[24:25], v254 offset0:2 offset1:6
	ds_read2_b32 v[26:27], v254 offset0:3 offset1:7
	ds_read2_b32 v[28:29], v254 offset0:8 offset1:12
	ds_read2_b32 v[30:31], v254 offset0:9 offset1:13
	ds_read2_b32 v[52:53], v254 offset0:10 offset1:14
	ds_read2_b32 v[54:55], v254 offset0:11 offset1:15
	ds_read2_b32 v[56:57], v254 offset0:16 offset1:20
	ds_read2_b32 v[58:59], v254 offset0:17 offset1:21
	ds_read2_b32 v[60:61], v254 offset0:18 offset1:22
	ds_read2_b32 v[62:63], v254 offset0:19 offset1:23
	ds_read2_b32 v[64:65], v254 offset0:24 offset1:28
	ds_read2_b32 v[66:67], v254 offset0:25 offset1:29
	ds_read2_b32 v[214:215], v254 offset0:26 offset1:30
	ds_read2_b32 v[252:253], v254 offset0:27 offset1:31
	s_waitcnt lgkmcnt(8)
	v_pk_mul_f32 v[22:23], v[36:37], v[22:23]
	v_pk_mul_f32 v[30:31], v[44:45], v[30:31]
	v_pk_fma_f32 v[22:23], v[34:35], v[20:21], v[22:23]
	v_pk_fma_f32 v[30:31], v[42:43], v[28:29], v[30:31]
	v_pk_fma_f32 v[22:23], v[38:39], v[24:25], v[22:23]
	v_pk_fma_f32 v[30:31], v[46:47], v[52:53], v[30:31]
	v_pk_fma_f32 v[22:23], v[40:41], v[26:27], v[22:23]
	v_pk_fma_f32 v[30:31], v[48:49], v[54:55], v[30:31]
	v_add_f32_e32 v19, v50, v22
	v_add_f32_e32 v19, v19, v23
	v_add_f32_e32 v19, v19, v30
	v_add_f32_e32 v19, v19, v31
	ds_read2_b32 v[20:21], v254 offset0:32 offset1:36
	ds_read2_b32 v[22:23], v254 offset0:33 offset1:37
	ds_read2_b32 v[24:25], v254 offset0:34 offset1:38
	ds_read2_b32 v[26:27], v254 offset0:35 offset1:39
	ds_read2_b32 v[28:29], v254 offset0:40 offset1:44
	ds_read2_b32 v[30:31], v254 offset0:41 offset1:45
	ds_read2_b32 v[52:53], v254 offset0:42 offset1:46
	ds_read2_b32 v[54:55], v254 offset0:43 offset1:47
	s_waitcnt lgkmcnt(8)
	v_min_f32_e32 v51, 0, v19
	v_pk_mul_f32 v[58:59], v[36:37], v[58:59]
	v_mul_f32_e64 v68, |v19|, s17
	v_pk_mul_f32 v[66:67], v[44:45], v[66:67]
	v_exp_f32_e32 v68, v68
	v_pk_fma_f32 v[58:59], v[34:35], v[56:57], v[58:59]
	v_pk_fma_f32 v[66:67], v[42:43], v[64:65], v[66:67]
	v_add_f32_e32 v68, 1.0, v68
	v_pk_fma_f32 v[58:59], v[38:39], v[60:61], v[58:59]
	v_log_f32_e32 v68, v68
	v_pk_fma_f32 v[66:67], v[46:47], v[214:215], v[66:67]
	v_pk_fma_f32 v[58:59], v[40:41], v[62:63], v[58:59]
	v_mul_f32_e32 v216, 0x3f317217, v68
	v_pk_fma_f32 v[66:67], v[48:49], v[252:253], v[66:67]
	v_fma_f32 v216, v68, s18, -v216
	v_add_f32_e32 v219, v50, v58
	v_fmac_f32_e32 v216, 0x3377d1cf, v68
	v_add_f32_e32 v219, v219, v59
	v_fmac_f32_e32 v216, 0x3f317217, v68
	v_add_f32_e32 v219, v219, v66
	v_sub_f32_e32 v51, v51, v216
	v_add_f32_e32 v219, v219, v67
	v_fmac_f32_e32 v16, 0x3d800000, v51
	ds_write_b32 v18, v16
	ds_read2_b32 v[56:57], v254 offset0:48 offset1:52
	ds_read2_b32 v[58:59], v254 offset0:49 offset1:53
	ds_read2_b32 v[60:61], v254 offset0:50 offset1:54
	ds_read2_b32 v[62:63], v254 offset0:51 offset1:55
	ds_read2_b32 v[64:65], v254 offset0:56 offset1:60
	ds_read2_b32 v[66:67], v254 offset0:57 offset1:61
	ds_read2_b32 v[214:215], v254 offset0:58 offset1:62
	ds_read2_b32 v[252:253], v254 offset0:59 offset1:63
	s_waitcnt lgkmcnt(8)
	v_min_f32_e32 v225, 0, v219
	v_pk_mul_f32 v[22:23], v[36:37], v[22:23]
	v_mul_f32_e64 v226, |v219|, s17
	v_pk_mul_f32 v[30:31], v[44:45], v[30:31]
	v_exp_f32_e32 v226, v226
	v_pk_fma_f32 v[22:23], v[34:35], v[20:21], v[22:23]
	v_pk_fma_f32 v[30:31], v[42:43], v[28:29], v[30:31]
	v_add_f32_e32 v226, 1.0, v226
	v_pk_fma_f32 v[22:23], v[38:39], v[24:25], v[22:23]
	v_log_f32_e32 v226, v226
	v_pk_fma_f32 v[30:31], v[46:47], v[52:53], v[30:31]
	v_pk_fma_f32 v[22:23], v[40:41], v[26:27], v[22:23]
	v_mul_f32_e32 v251, 0x3f317217, v226
	v_pk_fma_f32 v[30:31], v[48:49], v[54:55], v[30:31]
	v_fma_f32 v251, v226, s18, -v251
	v_add_f32_e32 v19, v50, v22
	v_fmac_f32_e32 v251, 0x3377d1cf, v226
	v_add_f32_e32 v19, v19, v23
	v_fmac_f32_e32 v251, 0x3f317217, v226
	v_add_f32_e32 v19, v19, v30
	v_sub_f32_e32 v225, v225, v251
	v_add_f32_e32 v19, v19, v31
	v_fmac_f32_e32 v16, 0x3d800000, v225
	ds_write_b32 v18, v16 offset:516
	s_waitcnt lgkmcnt(1)
	v_min_f32_e32 v51, 0, v19
	v_pk_mul_f32 v[58:59], v[36:37], v[58:59]
	v_mul_f32_e64 v68, |v19|, s17
	v_pk_mul_f32 v[66:67], v[44:45], v[66:67]
	v_exp_f32_e32 v68, v68
	v_pk_fma_f32 v[58:59], v[34:35], v[56:57], v[58:59]
	v_pk_fma_f32 v[66:67], v[42:43], v[64:65], v[66:67]
	v_add_f32_e32 v68, 1.0, v68
	v_pk_fma_f32 v[58:59], v[38:39], v[60:61], v[58:59]
	v_log_f32_e32 v68, v68
	v_pk_fma_f32 v[66:67], v[46:47], v[214:215], v[66:67]
	v_pk_fma_f32 v[58:59], v[40:41], v[62:63], v[58:59]
	v_mul_f32_e32 v216, 0x3f317217, v68
	v_pk_fma_f32 v[66:67], v[48:49], v[252:253], v[66:67]
	v_fma_f32 v216, v68, s18, -v216
	v_add_f32_e32 v219, v50, v58
	v_fmac_f32_e32 v216, 0x3377d1cf, v68
	v_add_f32_e32 v219, v219, v59
	v_fmac_f32_e32 v216, 0x3f317217, v68
	v_add_f32_e32 v219, v219, v66
	v_sub_f32_e32 v51, v51, v216
	v_add_f32_e32 v219, v219, v67
	v_fmac_f32_e32 v16, 0x3d800000, v51
	ds_write_b32 v18, v16 offset:1032
	v_min_f32_e32 v225, 0, v219
	v_mul_f32_e64 v226, |v219|, s17
	v_exp_f32_e32 v226, v226
	s_nop 0
	v_add_f32_e32 v226, 1.0, v226
	v_log_f32_e32 v226, v226
	s_nop 0
	v_mul_f32_e32 v251, 0x3f317217, v226
	v_fma_f32 v251, v226, s18, -v251
	v_fmac_f32_e32 v251, 0x3377d1cf, v226
	v_fmac_f32_e32 v251, 0x3f317217, v226
	v_sub_f32_e32 v225, v225, v251
	v_fmac_f32_e32 v16, 0x3d800000, v225
	ds_write_b32 v18, v16 offset:1548
	s_add_i32 s7, s7, -4
	v_add_u32_e32 v18, 0x810, v18
	v_add_u32_e32 v17, 0x100, v17
	s_cmp_eq_u32 s7, 0
	s_cbranch_scc0 .LBB0_352
	s_branch .Ls1pad
	s_nop 0
	s_nop 0
	s_nop 0
	s_nop 0
	s_nop 0
	s_nop 0
	s_nop 0
	s_nop 0
	s_nop 0
	s_nop 0
	s_nop 0
	s_nop 0
	s_nop 0
	s_nop 0
	s_nop 0
	s_nop 0
	s_nop 0
	s_nop 0
	s_nop 0
	s_nop 0
	s_nop 0
	s_nop 0
	s_nop 0
	s_nop 0
	s_nop 0
	s_nop 0
	s_nop 0
	s_nop 0
	s_nop 0
	s_nop 0
	s_nop 0
	s_nop 0
	s_nop 0
	s_nop 0
	s_nop 0
	s_nop 0
	s_nop 0
	s_nop 0
	s_nop 0
	s_nop 0
	s_nop 0
	s_nop 0
	s_nop 0
	s_nop 0
	s_nop 0
	s_nop 0
	s_nop 0
	s_nop 0
	s_nop 0
	s_nop 0
	s_nop 0
	s_nop 0
	s_nop 0
	s_nop 0
	s_nop 0
	s_nop 0
	s_nop 0
	s_nop 0
	s_nop 0
	s_nop 0
	s_nop 0
	s_nop 0
	s_nop 0
	s_nop 0
	s_nop 0
	s_nop 0
	s_nop 0
	s_nop 0
	s_nop 0
	s_nop 0
	s_nop 0
	s_nop 0
	s_nop 0
	s_nop 0
	s_nop 0
	s_nop 0
	s_nop 0
	s_nop 0
	s_nop 0
	s_nop 0
	s_nop 0
	s_nop 0
	s_nop 0
	s_nop 0
	s_nop 0
	s_nop 0
	s_nop 0
	s_nop 0
	s_nop 0
	s_nop 0
	s_nop 0
	s_nop 0
	s_nop 0
	s_nop 0
	s_nop 0
	s_nop 0
	s_nop 0
	s_nop 0
	s_nop 0
; __device__ __forceinline__ unsigned cvt_pk_bf16(float lo, float hi) { unsigned r; asm volatile("v_cvt_pk_bf16_f32 %0, %1, %2" : "=v"(r) : "v"(lo), "v"(hi)); return r; }
; #define LAS __attribute__((address_space(3)))
; __device__ __forceinline__ float bf_lo(unsigned w) { return __uint_as_float(w << 16); }
; __device__ __forceinline__ float bf_hi(unsigned w) { return __uint_as_float(w & 0xffff0000u); }
; __device__ __forceinline__ void gla_passA(LAS unsigned char* lds, int uidx, const bf16_t* PR, const float* GLRP, const float* w2, const float* gb,
;                                           bf16_t* SUB, float* EB, bf16_t* QT, bf16_t* AM, int tid, int wid, int lane) {
;     ...
;       Tt[tg * 128 + kcol] = run; }
;     __syncthreads();
;     {
;         const int j = tid >> 3, kr = (tid & 7) * 16, jg = j >> 4;
;         const float scale = 0.08838834764831845f;
;         u32x4 oq[2], ok[2], oh[2];
; #pragma unroll
;         for (int e4 = 0; e4 < 4; ++e4) {
;             const f32x4 t0 = *(const LAS f32x4*)(Tt + 0 * 128 + kr + 4 * e4), t1 = *(const LAS f32x4*)(Tt + 1 * 128 + kr + 4 * e4), t2 = *(const LAS f32x4*)(Tt + 2 * 128 + kr + 4 * e4), t3 = *(const LAS f32x4*)(Tt + 3 * 128 + kr + 4 * e4);
;             const f32x4 zz = {0.f, 0.f, 0.f, 0.f}; const f32x4 off = (jg > 0 ? t0 : zz) + (jg > 1 ? t1 : zz) + (jg > 2 ? t2 : zz), bc = (t0 + t1) + (t2 + t3);
; #pragma unroll
;             for (int eh = 0; eh < 2; ++eh) { const int e2 = 2 * e4 + eh; const unsigned qw = e2 < 4 ? qa[e2] : qb[e2 - 4], kw = e2 < 4 ? ka[e2] : kb[e2 - 4];
;                 const int k = kr + 2 * e2;
;                 const float b0 = Bc[j * 129 + k] + off[2 * eh], b1 = Bc[j * 129 + k + 1] + off[2 * eh + 1], c0 = bc[2 * eh], c1 = bc[2 * eh + 1];
;                 const float q0 = bf_lo(qw) * scale * __expf(b0), q1 = bf_hi(qw) * scale * __expf(b1);
;                 const float k0 = bf_lo(kw), k1 = bf_hi(kw);
;                 const unsigned pq = cvt_pk_bf16(q0, q1), pk = cvt_pk_bf16(k0 * __expf(-b0), k1 * __expf(-b1)), ph = cvt_pk_bf16(k0 * __expf(c0 - b0), k1 * __expf(c1 - b1));
;                 if (e2 < 4) { oq[0][e2] = pq; ok[0][e2] = pk; oh[0][e2] = ph; } else { oq[1][e2 - 4] = pq; ok[1][e2 - 4] = pk; oh[1][e2 - 4] = ph; } }
;         }
.Ls1pad:
	ds_write_b32 v122, v16
	s_waitcnt lgkmcnt(0)
	s_barrier
	ds_read_b128 v[16:19], v123
	ds_read_b128 v[20:23], v124
	ds_read_b128 v[24:27], v125
	ds_read_b128 v[28:31], v126
	s_lshl_b32 s10, s6, 1
	s_waitcnt lgkmcnt(3)
	v_cndmask_b32_e64 v35, 0, v19, s[44:45]
	v_cndmask_b32_e64 v34, 0, v18, s[44:45]
	v_cndmask_b32_e64 v37, 0, v17, s[44:45]
	v_cndmask_b32_e64 v36, 0, v16, s[44:45]
	s_waitcnt lgkmcnt(2)
	v_cndmask_b32_e64 v41, 0, v21, s[46:47]
	v_cndmask_b32_e64 v40, 0, v20, s[46:47]
	v_pk_add_f32 v[18:19], v[18:19], v[22:23]
	v_pk_add_f32 v[16:17], v[16:17], v[20:21]
	s_waitcnt lgkmcnt(0)
	v_pk_add_f32 v[20:21], v[26:27], v[30:31]
	v_cndmask_b32_e64 v39, 0, v23, s[46:47]
	v_pk_add_f32 v[18:19], v[18:19], v[20:21]
	ds_read2_b32 v[20:21], v127 offset1:1
	v_cndmask_b32_e64 v38, 0, v22, s[46:47]
	v_pk_add_f32 v[36:37], v[36:37], v[40:41]
	v_pk_add_f32 v[34:35], v[34:35], v[38:39]
	v_cndmask_b32_e64 v39, 0, v25, s[48:49]
	v_cndmask_b32_e64 v38, 0, v24, s[48:49]
	v_pk_add_f32 v[36:37], v[36:37], v[38:39]
	v_pk_add_f32 v[22:23], v[24:25], v[28:29]
	s_waitcnt lgkmcnt(0)
	v_add_f32_e32 v20, v20, v36
	v_pk_add_f32 v[16:17], v[16:17], v[22:23]
	v_mul_f32_e32 v23, 0x3fb8aa3b, v20
	v_exp_f32_e32 v23, v23
	v_lshlrev_b32_e32 v22, 16, v12
	v_add_f32_e32 v21, v37, v21
	v_mul_f32_e32 v22, 0x3db504f3, v22
	v_mul_f32_e32 v22, v22, v23
	v_mul_f32_e32 v23, 0x3fb8aa3b, v21
	v_exp_f32_e32 v23, v23
	v_and_b32_e32 v12, 0xffff0000, v12
	v_mul_f32_e32 v12, 0x3db504f3, v12
	v_sub_f32_e32 v16, v16, v20
	v_mul_f32_e32 v12, v12, v23
	v_lshlrev_b32_e32 v23, 16, v8
	v_and_b32_e32 v24, 0xffff0000, v8
	v_cvt_pk_bf16_f32 v8, v22, v12
	v_mul_f32_e32 v12, 0xbfb8aa3b, v20
	v_mul_f32_e32 v16, 0x3fb8aa3b, v16
	v_sub_f32_e32 v17, v17, v21
	v_exp_f32_e32 v12, v12
	v_mul_f32_e32 v22, 0xbfb8aa3b, v21
	v_exp_f32_e32 v16, v16
	v_mul_f32_e32 v17, 0x3fb8aa3b, v17
	v_exp_f32_e32 v22, v22
	v_exp_f32_e32 v17, v17
	v_mul_f32_e32 v12, v12, v23
	v_mul_f32_e32 v16, v16, v23
	v_mul_f32_e32 v22, v22, v24
	v_cvt_pk_bf16_f32 v12, v12, v22
	v_mul_f32_e32 v17, v17, v24
	v_cvt_pk_bf16_f32 v16, v16, v17
	ds_read2_b32 v[20:21], v127 offset0:2 offset1:3
	v_cndmask_b32_e64 v41, 0, v27, s[48:49]
	v_cndmask_b32_e64 v40, 0, v26, s[48:49]
	v_pk_add_f32 v[34:35], v[34:35], v[40:41]
	v_and_b32_e32 v23, 0xffff0000, v9
	s_waitcnt lgkmcnt(0)
	v_add_f32_e32 v17, v34, v20
	v_mul_f32_e32 v22, 0x3fb8aa3b, v17
	v_exp_f32_e32 v22, v22
	v_add_f32_e32 v20, v35, v21
	v_lshlrev_b32_e32 v21, 16, v13
	v_mul_f32_e32 v21, 0x3db504f3, v21
	v_mul_f32_e32 v21, v21, v22
	v_mul_f32_e32 v22, 0x3fb8aa3b, v20
	v_exp_f32_e32 v22, v22
	v_and_b32_e32 v13, 0xffff0000, v13
	v_mul_f32_e32 v13, 0x3db504f3, v13
	s_lshl_b32 s7, s67, 2
	v_mul_f32_e32 v13, v13, v22
	v_lshlrev_b32_e32 v22, 16, v9
	v_cvt_pk_bf16_f32 v9, v21, v13
	v_mul_f32_e32 v13, 0xbfb8aa3b, v17
	v_sub_f32_e32 v17, v18, v17
	v_sub_f32_e32 v18, v19, v20
	v_mul_f32_e32 v21, 0xbfb8aa3b, v20
	v_mul_f32_e32 v17, 0x3fb8aa3b, v17
	v_mul_f32_e32 v18, 0x3fb8aa3b, v18
	v_exp_f32_e32 v13, v13
	v_exp_f32_e32 v21, v21
	v_exp_f32_e32 v17, v17
	v_exp_f32_e32 v18, v18
	v_mul_f32_e32 v13, v13, v22
	v_mul_f32_e32 v21, v21, v23
	v_mul_f32_e32 v17, v17, v22
	v_mul_f32_e32 v18, v18, v23
	v_cvt_pk_bf16_f32 v13, v13, v21
	v_cvt_pk_bf16_f32 v17, v17, v18
	ds_read_b128 v[18:21], v123 offset:16
	ds_read_b128 v[22:25], v124 offset:16
	ds_read_b128 v[26:29], v125 offset:16
	ds_read_b128 v[34:37], v126 offset:16
	s_or_b32 s86, s7, s68
	s_waitcnt lgkmcnt(3)
	v_cndmask_b32_e64 v31, 0, v21, s[44:45]
	v_cndmask_b32_e64 v30, 0, v20, s[44:45]
	v_cndmask_b32_e64 v39, 0, v19, s[44:45]
	v_cndmask_b32_e64 v38, 0, v18, s[44:45]
	s_waitcnt lgkmcnt(2)
	v_cndmask_b32_e64 v43, 0, v23, s[46:47]
	v_cndmask_b32_e64 v42, 0, v22, s[46:47]
	v_pk_add_f32 v[20:21], v[20:21], v[24:25]
	v_pk_add_f32 v[18:19], v[18:19], v[22:23]
	s_waitcnt lgkmcnt(0)
	v_pk_add_f32 v[22:23], v[28:29], v[36:37]
	v_cndmask_b32_e64 v41, 0, v25, s[46:47]
	v_pk_add_f32 v[20:21], v[20:21], v[22:23]
	ds_read2_b32 v[22:23], v127 offset0:4 offset1:5
	v_cndmask_b32_e64 v40, 0, v24, s[46:47]
	v_pk_add_f32 v[38:39], v[38:39], v[42:43]
	v_pk_add_f32 v[30:31], v[30:31], v[40:41]
	v_cndmask_b32_e64 v41, 0, v27, s[48:49]
	v_cndmask_b32_e64 v40, 0, v26, s[48:49]
	v_pk_add_f32 v[38:39], v[38:39], v[40:41]
	v_pk_add_f32 v[24:25], v[26:27], v[34:35]
	s_waitcnt lgkmcnt(0)
	v_add_f32_e32 v22, v22, v38
	v_pk_add_f32 v[18:19], v[18:19], v[24:25]
	v_mul_f32_e32 v25, 0x3fb8aa3b, v22
	v_exp_f32_e32 v25, v25
	v_lshlrev_b32_e32 v24, 16, v14
	v_add_f32_e32 v23, v39, v23
	v_mul_f32_e32 v24, 0x3db504f3, v24
	v_mul_f32_e32 v24, v24, v25
	v_mul_f32_e32 v25, 0x3fb8aa3b, v23
	v_exp_f32_e32 v25, v25
	v_and_b32_e32 v14, 0xffff0000, v14
	v_mul_f32_e32 v14, 0x3db504f3, v14
	v_sub_f32_e32 v18, v18, v22
	v_mul_f32_e32 v14, v14, v25
	v_lshlrev_b32_e32 v25, 16, v10
	v_and_b32_e32 v26, 0xffff0000, v10
	v_cvt_pk_bf16_f32 v10, v24, v14
	v_mul_f32_e32 v14, 0xbfb8aa3b, v22
	v_mul_f32_e32 v18, 0x3fb8aa3b, v18
	v_sub_f32_e32 v19, v19, v23
	v_exp_f32_e32 v14, v14
	v_mul_f32_e32 v24, 0xbfb8aa3b, v23
	v_exp_f32_e32 v18, v18
	v_mul_f32_e32 v19, 0x3fb8aa3b, v19
	v_exp_f32_e32 v24, v24
	v_exp_f32_e32 v19, v19
	v_mul_f32_e32 v14, v14, v25
	v_mul_f32_e32 v18, v18, v25
	v_mul_f32_e32 v24, v24, v26
	v_cvt_pk_bf16_f32 v14, v14, v24
	v_mul_f32_e32 v19, v19, v26
	v_cvt_pk_bf16_f32 v18, v18, v19
	ds_read2_b32 v[22:23], v127 offset0:6 offset1:7
	v_cndmask_b32_e64 v43, 0, v29, s[48:49]
	v_cndmask_b32_e64 v42, 0, v28, s[48:49]
	v_pk_add_f32 v[30:31], v[30:31], v[42:43]
	v_and_b32_e32 v25, 0xffff0000, v11
	s_waitcnt lgkmcnt(0)
; __device__ __forceinline__ unsigned cvt_pk_bf16(float lo, float hi) { unsigned r; asm volatile("v_cvt_pk_bf16_f32 %0, %1, %2" : "=v"(r) : "v"(lo), "v"(hi)); return r; }
; #define LAS __attribute__((address_space(3)))
; __device__ __forceinline__ float bf_lo(unsigned w) { return __uint_as_float(w << 16); }
; __device__ __forceinline__ float bf_hi(unsigned w) { return __uint_as_float(w & 0xffff0000u); }
; __device__ __forceinline__ void gla_passA(LAS unsigned char* lds, int uidx, const bf16_t* PR, const float* GLRP, const float* w2, const float* gb,
;                                           bf16_t* SUB, float* EB, bf16_t* QT, bf16_t* AM, int tid, int wid, int lane) {
;     ...
;         for (int e4 = 0; e4 < 4; ++e4) {
;             const f32x4 t0 = *(const LAS f32x4*)(Tt + 0 * 128 + kr + 4 * e4), t1 = *(const LAS f32x4*)(Tt + 1 * 128 + kr + 4 * e4), t2 = *(const LAS f32x4*)(Tt + 2 * 128 + kr + 4 * e4), t3 = *(const LAS f32x4*)(Tt + 3 * 128 + kr + 4 * e4);
;             const f32x4 zz = {0.f, 0.f, 0.f, 0.f}; const f32x4 off = (jg > 0 ? t0 : zz) + (jg > 1 ? t1 : zz) + (jg > 2 ? t2 : zz), bc = (t0 + t1) + (t2 + t3);
; #pragma unroll
;             for (int eh = 0; eh < 2; ++eh) { const int e2 = 2 * e4 + eh; const unsigned qw = e2 < 4 ? qa[e2] : qb[e2 - 4], kw = e2 < 4 ? ka[e2] : kb[e2 - 4];
;                 const int k = kr + 2 * e2;
;                 const float b0 = Bc[j * 129 + k] + off[2 * eh], b1 = Bc[j * 129 + k + 1] + off[2 * eh + 1], c0 = bc[2 * eh], c1 = bc[2 * eh + 1];
;                 const float q0 = bf_lo(qw) * scale * __expf(b0), q1 = bf_hi(qw) * scale * __expf(b1);
;                 const float k0 = bf_lo(kw), k1 = bf_hi(kw);
;                 const unsigned pq = cvt_pk_bf16(q0, q1), pk = cvt_pk_bf16(k0 * __expf(-b0), k1 * __expf(-b1)), ph = cvt_pk_bf16(k0 * __expf(c0 - b0), k1 * __expf(c1 - b1));
;                 if (e2 < 4) { oq[0][e2] = pq; ok[0][e2] = pk; oh[0][e2] = ph; } else { oq[1][e2 - 4] = pq; ok[1][e2 - 4] = pk; oh[1][e2 - 4] = ph; } }
;         }
	v_add_f32_e32 v19, v30, v22
	v_mul_f32_e32 v24, 0x3fb8aa3b, v19
	v_exp_f32_e32 v24, v24
	v_add_f32_e32 v22, v31, v23
	v_lshlrev_b32_e32 v23, 16, v15
	v_mul_f32_e32 v23, 0x3db504f3, v23
	v_mul_f32_e32 v23, v23, v24
	v_mul_f32_e32 v24, 0x3fb8aa3b, v22
	v_exp_f32_e32 v24, v24
	v_and_b32_e32 v15, 0xffff0000, v15
	v_mul_f32_e32 v15, 0x3db504f3, v15
	v_mul_f32_e32 v15, v15, v24
	v_lshlrev_b32_e32 v24, 16, v11
	v_cvt_pk_bf16_f32 v11, v23, v15
	v_mul_f32_e32 v15, 0xbfb8aa3b, v19
	v_sub_f32_e32 v19, v20, v19
	v_sub_f32_e32 v20, v21, v22
	v_mul_f32_e32 v23, 0xbfb8aa3b, v22
	v_mul_f32_e32 v19, 0x3fb8aa3b, v19
	v_mul_f32_e32 v20, 0x3fb8aa3b, v20
	v_exp_f32_e32 v15, v15
	v_exp_f32_e32 v23, v23
	v_exp_f32_e32 v19, v19
	v_exp_f32_e32 v20, v20
	v_mul_f32_e32 v15, v15, v24
	v_mul_f32_e32 v23, v23, v25
	v_mul_f32_e32 v19, v19, v24
	v_mul_f32_e32 v20, v20, v25
	v_cvt_pk_bf16_f32 v15, v15, v23
	v_cvt_pk_bf16_f32 v19, v19, v20
	ds_read_b128 v[20:23], v123 offset:32
	ds_read_b128 v[24:27], v124 offset:32
	ds_read_b128 v[28:31], v125 offset:32
	ds_read_b128 v[34:37], v126 offset:32
	s_waitcnt lgkmcnt(3)
	v_cndmask_b32_e64 v39, 0, v23, s[44:45]
	v_cndmask_b32_e64 v38, 0, v22, s[44:45]
	v_cndmask_b32_e64 v41, 0, v21, s[44:45]
	v_cndmask_b32_e64 v40, 0, v20, s[44:45]
	s_waitcnt lgkmcnt(2)
	v_cndmask_b32_e64 v45, 0, v25, s[46:47]
	v_cndmask_b32_e64 v44, 0, v24, s[46:47]
	v_pk_add_f32 v[22:23], v[22:23], v[26:27]
	v_pk_add_f32 v[20:21], v[20:21], v[24:25]
	s_waitcnt lgkmcnt(0)
	v_pk_add_f32 v[24:25], v[30:31], v[36:37]
	v_cndmask_b32_e64 v43, 0, v27, s[46:47]
	v_pk_add_f32 v[22:23], v[22:23], v[24:25]
	ds_read2_b32 v[24:25], v127 offset0:8 offset1:9
	v_cndmask_b32_e64 v42, 0, v26, s[46:47]
	v_pk_add_f32 v[40:41], v[40:41], v[44:45]
	v_pk_add_f32 v[38:39], v[38:39], v[42:43]
	v_cndmask_b32_e64 v43, 0, v29, s[48:49]
	v_cndmask_b32_e64 v42, 0, v28, s[48:49]
	v_pk_add_f32 v[40:41], v[40:41], v[42:43]
	v_pk_add_f32 v[26:27], v[28:29], v[34:35]
	s_waitcnt lgkmcnt(0)
	v_add_f32_e32 v24, v24, v40
	v_pk_add_f32 v[20:21], v[20:21], v[26:27]
	v_mul_f32_e32 v27, 0x3fb8aa3b, v24
	v_exp_f32_e32 v27, v27
	v_lshlrev_b32_e32 v26, 16, v4
	v_add_f32_e32 v25, v41, v25
	v_mul_f32_e32 v26, 0x3db504f3, v26
	v_mul_f32_e32 v26, v26, v27
	v_mul_f32_e32 v27, 0x3fb8aa3b, v25
	v_exp_f32_e32 v27, v27
	v_and_b32_e32 v4, 0xffff0000, v4
	v_mul_f32_e32 v4, 0x3db504f3, v4
	v_sub_f32_e32 v20, v20, v24
	v_mul_f32_e32 v4, v4, v27
	v_lshlrev_b32_e32 v27, 16, v0
	v_and_b32_e32 v28, 0xffff0000, v0
	v_cvt_pk_bf16_f32 v0, v26, v4
	v_mul_f32_e32 v4, 0xbfb8aa3b, v24
	v_mul_f32_e32 v20, 0x3fb8aa3b, v20
	v_sub_f32_e32 v21, v21, v25
	v_exp_f32_e32 v4, v4
	v_mul_f32_e32 v26, 0xbfb8aa3b, v25
	v_exp_f32_e32 v20, v20
	v_mul_f32_e32 v21, 0x3fb8aa3b, v21
	v_exp_f32_e32 v26, v26
	v_exp_f32_e32 v21, v21
	v_mul_f32_e32 v4, v4, v27
	v_mul_f32_e32 v20, v20, v27
	v_mul_f32_e32 v26, v26, v28
	v_cvt_pk_bf16_f32 v4, v4, v26
	v_mul_f32_e32 v21, v21, v28
	v_cvt_pk_bf16_f32 v20, v20, v21
	ds_read2_b32 v[24:25], v127 offset0:10 offset1:11
	v_cndmask_b32_e64 v45, 0, v31, s[48:49]
	v_cndmask_b32_e64 v44, 0, v30, s[48:49]
	v_pk_add_f32 v[38:39], v[38:39], v[44:45]
	v_and_b32_e32 v27, 0xffff0000, v1
	s_waitcnt lgkmcnt(0)
	v_add_f32_e32 v21, v38, v24
	v_mul_f32_e32 v26, 0x3fb8aa3b, v21
	v_exp_f32_e32 v26, v26
	v_add_f32_e32 v24, v39, v25
	v_lshlrev_b32_e32 v25, 16, v5
	v_mul_f32_e32 v25, 0x3db504f3, v25
	v_mul_f32_e32 v25, v25, v26
	v_mul_f32_e32 v26, 0x3fb8aa3b, v24
	v_exp_f32_e32 v26, v26
	v_and_b32_e32 v5, 0xffff0000, v5
	v_mul_f32_e32 v5, 0x3db504f3, v5
	v_mul_f32_e32 v5, v5, v26
	v_lshlrev_b32_e32 v26, 16, v1
	v_cvt_pk_bf16_f32 v1, v25, v5
	v_mul_f32_e32 v5, 0xbfb8aa3b, v21
	v_sub_f32_e32 v21, v22, v21
	v_sub_f32_e32 v22, v23, v24
	v_mul_f32_e32 v25, 0xbfb8aa3b, v24
	v_mul_f32_e32 v21, 0x3fb8aa3b, v21
	v_mul_f32_e32 v22, 0x3fb8aa3b, v22
	v_exp_f32_e32 v5, v5
	v_exp_f32_e32 v25, v25
	v_exp_f32_e32 v21, v21
	v_exp_f32_e32 v22, v22
	v_mul_f32_e32 v5, v5, v26
	v_mul_f32_e32 v25, v25, v27
	v_mul_f32_e32 v21, v21, v26
	v_mul_f32_e32 v22, v22, v27
	v_cvt_pk_bf16_f32 v5, v5, v25
	v_cvt_pk_bf16_f32 v21, v21, v22
	ds_read_b128 v[22:25], v123 offset:48
	ds_read_b128 v[26:29], v124 offset:48
	ds_read_b128 v[34:37], v125 offset:48
	ds_read_b128 v[38:41], v126 offset:48
	s_waitcnt lgkmcnt(3)
; __device__ __forceinline__ unsigned cvt_pk_bf16(float lo, float hi) { unsigned r; asm volatile("v_cvt_pk_bf16_f32 %0, %1, %2" : "=v"(r) : "v"(lo), "v"(hi)); return r; }
; #define LAS __attribute__((address_space(3)))
; __device__ __forceinline__ void gla_passA(LAS unsigned char* lds, int uidx, const bf16_t* PR, const float* GLRP, const float* w2, const float* gb,
;                                           bf16_t* SUB, float* EB, bf16_t* QT, bf16_t* AM, int tid, int wid, int lane) {
;     ...
;         for (int e4 = 0; e4 < 4; ++e4) {
;             const f32x4 t0 = *(const LAS f32x4*)(Tt + 0 * 128 + kr + 4 * e4), t1 = *(const LAS f32x4*)(Tt + 1 * 128 + kr + 4 * e4), t2 = *(const LAS f32x4*)(Tt + 2 * 128 + kr + 4 * e4), t3 = *(const LAS f32x4*)(Tt + 3 * 128 + kr + 4 * e4);
;             const f32x4 zz = {0.f, 0.f, 0.f, 0.f}; const f32x4 off = (jg > 0 ? t0 : zz) + (jg > 1 ? t1 : zz) + (jg > 2 ? t2 : zz), bc = (t0 + t1) + (t2 + t3);
; #pragma unroll
;             for (int eh = 0; eh < 2; ++eh) { const int e2 = 2 * e4 + eh; const unsigned qw = e2 < 4 ? qa[e2] : qb[e2 - 4], kw = e2 < 4 ? ka[e2] : kb[e2 - 4];
;                 const int k = kr + 2 * e2;
;                 const float b0 = Bc[j * 129 + k] + off[2 * eh], b1 = Bc[j * 129 + k + 1] + off[2 * eh + 1], c0 = bc[2 * eh], c1 = bc[2 * eh + 1];
;                 const float q0 = bf_lo(qw) * scale * __expf(b0), q1 = bf_hi(qw) * scale * __expf(b1);
;                 const float k0 = bf_lo(kw), k1 = bf_hi(kw);
;                 const unsigned pq = cvt_pk_bf16(q0, q1), pk = cvt_pk_bf16(k0 * __expf(-b0), k1 * __expf(-b1)), ph = cvt_pk_bf16(k0 * __expf(c0 - b0), k1 * __expf(c1 - b1));
;                 if (e2 < 4) { oq[0][e2] = pq; ok[0][e2] = pk; oh[0][e2] = ph; } else { oq[1][e2 - 4] = pq; ok[1][e2 - 4] = pk; oh[1][e2 - 4] = ph; } }
;         }
;         *(LAS u32x4*)(Qs + j * 136 + kr) = oq[0]; *(LAS u32x4*)(Qs + j * 136 + kr + 8) = oq[1];
;         *(LAS u32x4*)(Ks + j * 136 + kr) = ok[0]; *(LAS u32x4*)(Ks + j * 136 + kr + 8) = ok[1];
;         *(LAS u32x4*)(Kh + j * 136 + kr) = oh[0]; *(LAS u32x4*)(Kh + j * 136 + kr + 8) = oh[1];
;         bf16_t* qt = QT + (size_t)(tok0 + j) * QKD + h * DK + kr; *(u32x4*)qt = oq[0]; *(u32x4*)(qt + 8) = oq[1];
;         if (tid < DK) EB[((size_t)bh * NCH + c) * DK + tid] = __expf((Tt[tid] + Tt[128 + tid]) + (Tt[256 + tid] + Tt[384 + tid]));
;     }
	v_cndmask_b32_e64 v31, 0, v25, s[44:45]
	v_cndmask_b32_e64 v30, 0, v24, s[44:45]
	v_cndmask_b32_e64 v43, 0, v23, s[44:45]
	v_cndmask_b32_e64 v42, 0, v22, s[44:45]
	s_waitcnt lgkmcnt(2)
	v_cndmask_b32_e64 v47, 0, v27, s[46:47]
	v_cndmask_b32_e64 v46, 0, v26, s[46:47]
	v_pk_add_f32 v[24:25], v[24:25], v[28:29]
	v_pk_add_f32 v[22:23], v[22:23], v[26:27]
	s_waitcnt lgkmcnt(0)
	v_pk_add_f32 v[26:27], v[36:37], v[40:41]
	v_cndmask_b32_e64 v45, 0, v29, s[46:47]
	v_pk_add_f32 v[24:25], v[24:25], v[26:27]
	ds_read2_b32 v[26:27], v127 offset0:12 offset1:13
	v_cndmask_b32_e64 v44, 0, v28, s[46:47]
	v_pk_add_f32 v[42:43], v[42:43], v[46:47]
	v_pk_add_f32 v[30:31], v[30:31], v[44:45]
	v_cndmask_b32_e64 v45, 0, v35, s[48:49]
	v_cndmask_b32_e64 v44, 0, v34, s[48:49]
	v_pk_add_f32 v[42:43], v[42:43], v[44:45]
	v_pk_add_f32 v[28:29], v[34:35], v[38:39]
	s_waitcnt lgkmcnt(0)
	v_add_f32_e32 v26, v26, v42
	v_pk_add_f32 v[22:23], v[22:23], v[28:29]
	v_mul_f32_e32 v29, 0x3fb8aa3b, v26
	v_exp_f32_e32 v29, v29
	v_lshlrev_b32_e32 v28, 16, v6
	v_add_f32_e32 v27, v43, v27
	v_mul_f32_e32 v28, 0x3db504f3, v28
	v_mul_f32_e32 v28, v28, v29
	v_mul_f32_e32 v29, 0x3fb8aa3b, v27
	v_exp_f32_e32 v29, v29
	v_and_b32_e32 v6, 0xffff0000, v6
	v_mul_f32_e32 v6, 0x3db504f3, v6
	v_sub_f32_e32 v22, v22, v26
	v_mul_f32_e32 v6, v6, v29
	v_lshlrev_b32_e32 v29, 16, v2
	v_and_b32_e32 v34, 0xffff0000, v2
	v_cvt_pk_bf16_f32 v2, v28, v6
	v_mul_f32_e32 v6, 0xbfb8aa3b, v26
	v_mul_f32_e32 v22, 0x3fb8aa3b, v22
	v_sub_f32_e32 v23, v23, v27
	v_exp_f32_e32 v6, v6
	v_mul_f32_e32 v28, 0xbfb8aa3b, v27
	v_exp_f32_e32 v22, v22
	v_mul_f32_e32 v23, 0x3fb8aa3b, v23
	v_exp_f32_e32 v28, v28
	v_exp_f32_e32 v23, v23
	v_mul_f32_e32 v6, v6, v29
	v_mul_f32_e32 v22, v22, v29
	v_mul_f32_e32 v28, v28, v34
	v_cvt_pk_bf16_f32 v6, v6, v28
	v_mul_f32_e32 v23, v23, v34
	v_cvt_pk_bf16_f32 v22, v22, v23
	ds_read2_b32 v[26:27], v127 offset0:14 offset1:15
	v_cndmask_b32_e64 v47, 0, v37, s[48:49]
	v_cndmask_b32_e64 v46, 0, v36, s[48:49]
	v_pk_add_f32 v[30:31], v[30:31], v[46:47]
	v_and_b32_e32 v29, 0xffff0000, v3
	s_waitcnt lgkmcnt(0)
	v_add_f32_e32 v23, v30, v26
	v_mul_f32_e32 v28, 0x3fb8aa3b, v23
	v_exp_f32_e32 v28, v28
	v_add_f32_e32 v26, v31, v27
	v_lshlrev_b32_e32 v27, 16, v7
	v_mul_f32_e32 v27, 0x3db504f3, v27
	v_mul_f32_e32 v27, v27, v28
	v_mul_f32_e32 v28, 0x3fb8aa3b, v26
	v_exp_f32_e32 v28, v28
	v_and_b32_e32 v7, 0xffff0000, v7
	v_mul_f32_e32 v7, 0x3db504f3, v7
	v_mul_f32_e32 v7, v7, v28
	v_lshlrev_b32_e32 v28, 16, v3
	v_cvt_pk_bf16_f32 v3, v27, v7
	v_mul_f32_e32 v7, 0xbfb8aa3b, v23
	v_sub_f32_e32 v23, v24, v23
	v_mul_f32_e32 v23, 0x3fb8aa3b, v23
	v_sub_f32_e32 v24, v25, v26
	v_exp_f32_e32 v7, v7
	v_mul_f32_e32 v27, 0xbfb8aa3b, v26
	v_exp_f32_e32 v23, v23
	v_mul_f32_e32 v24, 0x3fb8aa3b, v24
	v_exp_f32_e32 v27, v27
	v_exp_f32_e32 v24, v24
	v_mul_f32_e32 v7, v7, v28
	v_mul_f32_e32 v23, v23, v28
	v_mul_f32_e32 v27, v27, v29
	v_cvt_pk_bf16_f32 v7, v7, v27
	v_mul_f32_e32 v24, v24, v29
	v_cvt_pk_bf16_f32 v23, v23, v24
	ds_write_b128 v128, v[8:11] offset:33536
	ds_write_b128 v128, v[0:3] offset:33552
	ds_write_b128 v128, v[12:15] offset:50944
	ds_write_b128 v128, v[4:7] offset:50960
	ds_write_b128 v129, v[16:19]
	ds_write_b128 v129, v[20:23] offset:16
	v_lshlrev_b64 v[4:5], 10, v[32:33]
	v_lshl_add_u64 v[4:5], s[34:35], 0, v[4:5]
	v_lshl_add_u64 v[4:5], v[4:5], 0, s[10:11]
	v_lshl_add_u64 v[4:5], v[4:5], 0, v[168:169]
	global_store_dwordx4 v[4:5], v[8:11], off
	global_store_dwordx4 v[4:5], v[0:3], off offset:16
	s_and_saveexec_b64 s[6:7], s[42:43]
	s_xor_b64 s[6:7], exec, s[6:7]
	s_ashr_i32 s87, s86, 31
	s_or_saveexec_b64 s[6:7], s[6:7]
	v_mov_b64_e32 v[108:109], s[86:87]
	s_xor_b64 exec, exec, s[6:7]
	s_cbranch_execz .LBB0_348
	ds_read2st64_b32 v[0:1], v122 offset1:2
	ds_read2st64_b32 v[2:3], v122 offset0:4 offset1:6
	s_ashr_i32 s87, s86, 31
	s_lshl_b64 s[68:69], s[86:87], 14
	s_add_u32 s10, s9, s68
	s_waitcnt lgkmcnt(1)
	v_mov_b32_e32 v4, v0
	s_waitcnt lgkmcnt(0)
	v_mov_b32_e32 v5, v2
	v_mov_b32_e32 v2, v1
	v_pk_add_f32 v[0:1], v[4:5], v[2:3]
	s_addc_u32 s67, s30, s69
	v_add_f32_e32 v0, v0, v1
	v_mul_f32_e32 v0, 0x3fb8aa3b, v0
	v_exp_f32_e32 v2, v0
	s_lshl_b32 s68, s31, 9
	s_add_u32 s68, s10, s68
	s_addc_u32 s69, s67, 0
	v_lshl_add_u64 v[0:1], v[112:113], 2, s[68:69]
	v_mov_b64_e32 v[108:109], s[86:87]
	global_store_dword v[0:1], v2, off
	s_branch .LBB0_348
